# static s_setprio 1 for waves 0-3 (instead of 4-7) during the attention phase, on top of v61
# speedup vs baseline: 1.0018x; 1.0018x over previous
; #define LAS __attribute__((address_space(3)))
; __global__ void __launch_bounds__(512, 2) mega(Params p, int ph_lo, int ph_hi) {
;     ...
;     PHASE_BEGIN
;         LAS unsigned char* KS = lds + wave * (2 * 32 * HP * 2); LAS unsigned char* VS = KS + 32 * HP * 2;
;         for (int it = 0; it * G < 1024; ++it) {
;             const int item = (G == 256) ? ((bid & 7) * 128 + it * 32 + (bid >> 3)) : (bid + it * G);
;             if (item >= 1024) break;
;             const int b = item >> 9, h = (item >> 5) & 15, n = item & 31;
;             const int r0 = wave, r1 = wave + 8;
;             QTile t0, t1;
.LBB0_777:
	s_cmp_ge_u32 s96, 4
	s_cbranch_scc1 .Lat_noprio
	s_setprio 1
